# attention item prologue de-serialised: mask-word wait/LDS-store ladder moved behind the q / K,V tile load issue (counted vmcnt), phases 3 and 4
# speedup vs baseline: 1.0014x; 1.0014x over previous
.LBB0_791:
	s_or_b64 exec, exec, s[16:17]
	v_lshlrev_b32_e32 v8, 11, v3
	v_cndmask_b32_e64 v3, v18, v3, s[14:15]
	v_cndmask_b32_e64 v8, v8, v150, s[14:15]
	v_lshl_add_u32 v3, v3, 6, v8
	v_or_b32_e32 v19, v3, v142
	v_mov_b64_e32 v[8:9], s[92:93]
	v_add_u32_e32 v3, 0x100, v2
	v_mad_i64_i32 v[12:13], s[16:17], v19, s43, v[8:9]
	v_min_i32_e32 v8, 0x41f, v3
	v_add_u32_e32 v3, 0x200, v2
	v_min_i32_e32 v10, 0x41f, v3
	v_add_u32_e32 v3, 0x300, v2
	v_min_i32_e32 v14, 0x41f, v3
	v_ashrrev_i32_e32 v15, 31, v14
	v_add_u32_e32 v3, 0x400, v2
	v_ashrrev_i32_e32 v9, 31, v8
	v_ashrrev_i32_e32 v11, 31, v10
	v_lshl_add_u64 v[20:21], v[14:15], 3, v[12:13]
	v_min_i32_e32 v14, 0x41f, v3
	v_lshl_add_u64 v[8:9], v[8:9], 3, v[12:13]
	v_lshl_add_u64 v[10:11], v[10:11], 3, v[12:13]
	v_ashrrev_i32_e32 v15, 31, v14
	v_lshl_add_u64 v[22:23], v[14:15], 3, v[12:13]
	global_load_dwordx2 v[200:201], v[8:9], off nt
	global_load_dwordx2 v[202:203], v[10:11], off nt
	s_nop 0
	global_load_dwordx2 v[204:205], v[20:21], off nt
	global_load_dwordx2 v[206:207], v[22:23], off nt
	v_mov_b32_e32 v211, v2
	v_lshl_add_u32 v210, v2, 3, v141
	s_movk_i32 s16, 0x420
	v_cmp_gt_i32_e32 vcc, s16, v2
	s_and_saveexec_b64 s[16:17], vcc
	s_cbranch_execz .Lat3_m5skip
	v_ashrrev_i32_e32 v3, 31, v2
	v_lshl_add_u64 v[12:13], v[2:3], 3, v[12:13]
	global_load_dwordx2 v[208:209], v[12:13], off nt
.Lat3_m5skip:
	s_or_b64 exec, exec, s[16:17]
	v_and_b32_e32 v10, 0xffffffc0, v2
	v_and_b32_e32 v16, 31, v2
	v_bfe_u32 v17, v2, 5, 1
	v_add_u32_e32 v2, 1, v18
	v_cndmask_b32_e64 v111, v2, 33, s[14:15]
	v_or_b32_e32 v2, v19, v16
	v_ashrrev_i32_e32 v3, 31, v2
	v_lshl_add_u32 v126, v0, 8, v10
	v_lshlrev_b64 v[8:9], 10, v[2:3]
	v_ashrrev_i32_e32 v127, 31, v126
	v_lshlrev_b64 v[2:3], 11, v[2:3]
	v_lshl_add_u64 v[8:9], s[8:9], 0, v[8:9]
	v_lshlrev_b64 v[10:11], 1, v[126:127]
	v_lshl_add_u64 v[130:131], s[88:89], 0, v[2:3]
	v_lshl_add_u64 v[8:9], v[8:9], 0, v[10:11]
	v_lshlrev_b32_e32 v0, 3, v17
	v_lshlrev_b32_e32 v132, 4, v17
	v_mov_b32_e32 v133, v1
	v_lshl_add_u64 v[2:3], v[130:131], 0, v[10:11]
	v_lshl_add_u64 v[8:9], v[8:9], 0, v[132:133]
	v_lshl_add_u64 v[2:3], v[2:3], 0, v[0:1]
	s_mov_b64 s[16:17], 0x12e80400
	global_load_dwordx4 v[80:83], v[8:9], off
	global_load_dwordx4 v[84:87], v[8:9], off offset:32
	global_load_dwordx4 v[88:91], v[8:9], off offset:64
	global_load_dwordx4 v[92:95], v[8:9], off offset:96
	v_lshl_add_u64 v[8:9], v[2:3], 0, s[16:17]
	s_mov_b32 s16, 0x12e80000
	v_add_co_u32_e32 v2, vcc, s16, v2
	v_mov_b32_e32 v109, v1
	s_nop 0
	v_addc_co_u32_e32 v3, vcc, 0, v3, vcc
	global_load_dwordx2 v[124:125], v[8:9], off offset:16
	global_load_dwordx2 v[122:123], v[8:9], off offset:32
	global_load_dwordx2 v[120:121], v[8:9], off offset:48
	global_load_dwordx2 v[118:119], v[8:9], off offset:64
	global_load_dwordx2 v[128:129], v[2:3], off offset:1024
	global_load_dwordx2 v[116:117], v[8:9], off offset:80
	global_load_dwordx2 v[114:115], v[8:9], off offset:96
	global_load_dwordx2 v[112:113], v[8:9], off offset:112
	v_lshl_add_u64 v[2:3], v[4:5], 0, v[106:107]
	v_lshl_add_u64 v[2:3], v[2:3], 0, v[108:109]
	v_cndmask_b32_e64 v0, v145, v151, s[14:15]
	v_cmp_lt_u32_e32 vcc, 1, v111
	global_load_dwordx4 v[8:11], v[2:3], off
	v_mad_i64_i32 v[2:3], s[14:15], v0, v104, 0
	v_cndmask_b32_e64 v0, 0, 64, vcc
	v_lshl_add_u64 v[2:3], v[2:3], 1, v[6:7]
	v_add_u32_e32 v6, v0, v104
	v_ashrrev_i32_e32 v7, 31, v6
	v_lshlrev_b64 v[6:7], 7, v[6:7]
	v_add_u32_e32 v133, -1, v111
	v_lshl_add_u64 v[6:7], v[4:5], 0, v[6:7]
	v_min_u32_e32 v18, 2, v133
	v_lshl_add_u64 v[6:7], v[6:7], 0, v[108:109]
	v_lshlrev_b32_e32 v0, 1, v0
	global_load_dwordx4 v[48:51], v[6:7], off
	v_lshl_add_u64 v[6:7], v[2:3], 0, v[0:1]
	v_lshlrev_b32_e32 v0, 7, v18
	v_lshl_add_u64 v[134:135], v[2:3], 0, v[108:109]
	v_lshl_add_u64 v[2:3], v[2:3], 0, v[0:1]
	v_lshl_add_u64 v[6:7], v[6:7], 0, v[108:109]
	v_lshl_add_u64 v[2:3], v[2:3], 0, v[108:109]
	global_load_dwordx4 v[52:55], v[6:7], off
	global_load_dwordx4 v[100:103], v[2:3], off
	v_lshl_add_u32 v6, v18, 6, v104
	v_ashrrev_i32_e32 v7, 31, v6
	v_lshlrev_b64 v[6:7], 7, v[6:7]
	global_load_dwordx4 v[12:15], v[134:135], off
	v_lshl_add_u64 v[6:7], v[4:5], 0, v[6:7]
	v_lshl_add_u64 v[6:7], v[6:7], 0, v[108:109]
	global_load_dwordx4 v[96:99], v[6:7], off
	s_waitcnt vmcnt(18)
	s_movk_i32 s16, 0x420
	v_cmp_gt_i32_e32 vcc, s16, v211
	s_and_saveexec_b64 s[16:17], vcc
	ds_write_b64 v210, v[208:209]
	s_or_b64 exec, exec, s[16:17]
	s_movk_i32 s16, 0x320
	v_cmp_gt_i32_e32 vcc, s16, v211
	s_and_saveexec_b64 s[16:17], vcc
	ds_write_b64 v210, v[200:201] offset:2048
	s_or_b64 exec, exec, s[16:17]
	s_movk_i32 s16, 0x220
	v_cmp_gt_i32_e32 vcc, s16, v211
	s_and_saveexec_b64 s[16:17], vcc
	ds_write_b64 v210, v[202:203] offset:4096
	s_or_b64 exec, exec, s[16:17]
	s_movk_i32 s16, 0x120
	v_cmp_gt_i32_e32 vcc, s16, v211
	s_and_saveexec_b64 s[16:17], vcc
	ds_write_b64 v210, v[204:205] offset:6144
	s_or_b64 exec, exec, s[16:17]
	v_cmp_gt_i32_e32 vcc, 32, v211
	s_and_saveexec_b64 s[16:17], vcc
	ds_write_b64 v210, v[206:207] offset:8192
	s_or_b64 exec, exec, s[16:17]
	v_mov_b32_e32 v2, v1
	v_mov_b32_e32 v3, v1
	v_lshlrev_b32_e32 v136, 2, v17
	v_lshl_add_u64 v[138:139], v[4:5], 0, v[108:109]
	v_mul_u32_u24_e32 v109, 0x90, v16
	v_mad_u32_u24 v152, v16, s43, v141
	v_mov_b32_e32 v0, v1
	v_mov_b32_e32 v4, v1
	v_mov_b32_e32 v5, v1
	v_mov_b32_e32 v6, v1
	v_mov_b32_e32 v7, v1
	s_mov_b32 s19, 0
	v_mov_b32_e32 v154, 0xf149f2ca
	v_mov_b32_e32 v153, 0
	s_mov_b64 s[14:15], 0
	s_waitcnt vmcnt(5)
	ds_write_b128 v105, v[8:11]
	s_waitcnt vmcnt(1)
	ds_write_b128 v143, v[12:15]
	v_mov_b32_e32 v14, v1
	v_mov_b32_e32 v15, v1
	v_mov_b32_e32 v8, v1
	v_mov_b32_e32 v9, v1
	v_mov_b32_e32 v10, v1
	v_mov_b32_e32 v11, v1
	v_mov_b32_e32 v12, v1
	v_mov_b32_e32 v13, v1
	v_mov_b64_e32 v[30:31], v[14:15]
	v_mov_b64_e32 v[46:47], v[14:15]
	v_mov_b64_e32 v[28:29], v[12:13]
	v_mov_b64_e32 v[26:27], v[10:11]
	v_mov_b64_e32 v[24:25], v[8:9]
	v_mov_b64_e32 v[22:23], v[6:7]
	v_mov_b64_e32 v[20:21], v[4:5]
	v_mov_b64_e32 v[18:19], v[2:3]
	v_mov_b64_e32 v[16:17], v[0:1]
	v_mov_b64_e32 v[44:45], v[12:13]
	v_mov_b64_e32 v[42:43], v[10:11]
	v_mov_b64_e32 v[40:41], v[8:9]
	v_mov_b64_e32 v[38:39], v[6:7]
	v_mov_b64_e32 v[36:37], v[4:5]
	v_mov_b64_e32 v[34:35], v[2:3]
	v_mov_b64_e32 v[32:33], v[0:1]
	s_waitcnt lgkmcnt(0)
	s_barrier
	s_branch .LBB0_803

.LBB0_889:
	v_lshlrev_b32_e32 v2, 6, v130
	v_lshl_add_u32 v2, v12, 11, v2
	v_add_u32_e32 v8, 0x300, v172
	v_or_b32_e32 v13, v2, v183
	v_mov_b64_e32 v[2:3], s[92:93]
	v_min_i32_e32 v8, 0x41f, v8
	v_mad_i64_i32 v[6:7], s[18:19], v13, s33, v[2:3]
	v_add_u32_e32 v2, 0x100, v172
	v_add_u32_e32 v4, 0x200, v172
	v_ashrrev_i32_e32 v9, 31, v8
	v_min_i32_e32 v2, 0x41f, v2
	v_min_i32_e32 v4, 0x41f, v4
	v_lshl_add_u64 v[14:15], v[8:9], 3, v[6:7]
	v_add_u32_e32 v8, 0x400, v172
	v_ashrrev_i32_e32 v3, 31, v2
	v_ashrrev_i32_e32 v5, 31, v4
	v_min_i32_e32 v8, 0x41f, v8
	v_lshl_add_u64 v[2:3], v[2:3], 3, v[6:7]
	v_lshl_add_u64 v[4:5], v[4:5], 3, v[6:7]
	v_ashrrev_i32_e32 v9, 31, v8
	v_lshl_add_u64 v[16:17], v[8:9], 3, v[6:7]
	global_load_dwordx2 v[200:201], v[2:3], off nt
	global_load_dwordx2 v[202:203], v[4:5], off nt
	s_nop 0
	global_load_dwordx2 v[204:205], v[14:15], off nt
	global_load_dwordx2 v[206:207], v[16:17], off nt
	v_lshl_add_u32 v210, v172, 3, v182
	s_movk_i32 s18, 0x420
	v_cmp_gt_i32_e32 vcc, s18, v172
	s_and_saveexec_b64 s[18:19], vcc
	s_cbranch_execz .Lat4_m5skip
	v_ashrrev_i32_e32 v173, 31, v172
	v_lshl_add_u64 v[6:7], v[172:173], 3, v[6:7]
	global_load_dwordx2 v[208:209], v[6:7], off nt
.Lat4_m5skip:
	s_or_b64 exec, exec, s[18:19]
	v_and_b32_e32 v4, 31, v172
	v_and_b32_e32 v5, 0xffffffc0, v172
	v_or_b32_e32 v6, v13, v4
	v_ashrrev_i32_e32 v7, 31, v6
	v_lshl_add_u32 v118, v0, 8, v5
	v_lshl_add_u32 v2, v12, 1, v0
	v_lshlrev_b64 v[8:9], 10, v[6:7]
	v_ashrrev_i32_e32 v119, 31, v118
	v_lshlrev_b64 v[6:7], 11, v[6:7]
	v_bfe_u32 v22, v172, 5, 1
	v_ashrrev_i32_e32 v3, 31, v2
	v_readlane_b32 s18, v252, 51
	v_lshlrev_b64 v[12:13], 1, v[118:119]
	v_lshl_add_u64 v[120:121], s[88:89], 0, v[6:7]
	v_lshlrev_b64 v[10:11], 18, v[2:3]
	v_readlane_b32 s19, v252, 52
	v_lshlrev_b32_e32 v0, 3, v22
	v_lshl_add_u64 v[6:7], v[120:121], 0, v[12:13]
	v_lshl_add_u64 v[2:3], s[18:19], 0, v[10:11]
	v_lshl_add_u64 v[6:7], v[6:7], 0, v[0:1]
	s_mov_b64 s[18:19], 0x12e80400
	v_lshl_add_u64 v[16:17], v[6:7], 0, s[18:19]
	s_mov_b32 s18, 0x12e80000
	v_add_co_u32_e32 v18, vcc, s18, v6
	v_lshl_add_u64 v[8:9], s[8:9], 0, v[8:9]
	s_nop 0
	v_addc_co_u32_e32 v19, vcc, 0, v7, vcc
	v_lshl_add_u64 v[8:9], v[8:9], 0, v[12:13]
	v_lshlrev_b32_e32 v124, 4, v22
	v_mov_b32_e32 v125, v1
	v_lshl_add_u64 v[6:7], v[2:3], 0, v[164:165]
	v_mov_b32_e32 v169, v1
	v_cmp_lt_i32_e32 vcc, 0, v130
	v_lshl_add_u64 v[14:15], v[8:9], 0, v[124:125]
	v_lshl_add_u64 v[6:7], v[6:7], 0, v[168:169]
	v_lshl_add_u64 v[20:21], v[166:167], 0, v[10:11]
	v_cndmask_b32_e64 v0, 0, 64, vcc
	global_load_dwordx4 v[80:83], v[14:15], off offset:32
	global_load_dwordx4 v[84:87], v[14:15], off offset:64
	global_load_dwordx4 v[88:91], v[14:15], off offset:96
	global_load_dwordx2 v[116:117], v[16:17], off offset:16
	global_load_dwordx2 v[114:115], v[16:17], off offset:32
	global_load_dwordx2 v[112:113], v[16:17], off offset:48
	global_load_dwordx2 v[110:111], v[16:17], off offset:64
	global_load_dwordx2 v[108:109], v[16:17], off offset:80
	v_lshl_add_u64 v[126:127], v[20:21], 0, v[168:169]
	global_load_dwordx4 v[6:9], v[6:7], off
	s_nop 0
	global_load_dwordx4 v[92:95], v[14:15], off
	global_load_dwordx4 v[10:13], v[126:127], off
	global_load_dwordx2 v[122:123], v[18:19], off offset:1024
	global_load_dwordx2 v[106:107], v[16:17], off offset:96
	global_load_dwordx2 v[104:105], v[16:17], off offset:112
	v_min_i32_e32 v5, 2, v130
	v_add_u32_e32 v14, v0, v162
	v_ashrrev_i32_e32 v15, 31, v14
	v_lshlrev_b32_e32 v16, 6, v5
	v_lshlrev_b64 v[14:15], 7, v[14:15]
	v_add_u32_e32 v18, v16, v162
	v_lshl_add_u64 v[14:15], v[2:3], 0, v[14:15]
	v_ashrrev_i32_e32 v19, 31, v18
	v_ashrrev_i32_e32 v17, 31, v16
	v_lshl_add_u64 v[14:15], v[14:15], 0, v[168:169]
	v_lshlrev_b32_e32 v0, 1, v0
	v_lshlrev_b64 v[18:19], 7, v[18:19]
	v_lshl_add_u64 v[16:17], v[16:17], 1, v[20:21]
	global_load_dwordx4 v[48:51], v[14:15], off
	v_lshl_add_u64 v[14:15], v[20:21], 0, v[0:1]
	v_lshl_add_u64 v[18:19], v[2:3], 0, v[18:19]
	v_lshl_add_u64 v[16:17], v[16:17], 0, v[168:169]
	v_lshl_add_u64 v[14:15], v[14:15], 0, v[168:169]
	v_lshl_add_u64 v[18:19], v[18:19], 0, v[168:169]
	global_load_dwordx4 v[96:99], v[16:17], off
	global_load_dwordx4 v[52:55], v[14:15], off
	global_load_dwordx4 v[100:103], v[18:19], off
	s_waitcnt vmcnt(18)
	s_movk_i32 s18, 0x420
	v_cmp_gt_i32_e32 vcc, s18, v172
	s_and_saveexec_b64 s[18:19], vcc
	ds_write_b64 v210, v[208:209]
	s_or_b64 exec, exec, s[18:19]
	s_movk_i32 s18, 0x320
	v_cmp_gt_i32_e32 vcc, s18, v172
	s_and_saveexec_b64 s[18:19], vcc
	ds_write_b64 v210, v[200:201] offset:2048
	s_or_b64 exec, exec, s[18:19]
	s_movk_i32 s18, 0x220
	v_cmp_gt_i32_e32 vcc, s18, v172
	s_and_saveexec_b64 s[18:19], vcc
	ds_write_b64 v210, v[202:203] offset:4096
	s_or_b64 exec, exec, s[18:19]
	s_movk_i32 s18, 0x120
	v_cmp_gt_i32_e32 vcc, s18, v172
	s_and_saveexec_b64 s[18:19], vcc
	ds_write_b64 v210, v[204:205] offset:6144
	s_or_b64 exec, exec, s[18:19]
	v_cmp_gt_i32_e32 vcc, 32, v172
	s_and_saveexec_b64 s[18:19], vcc
	ds_write_b64 v210, v[206:207] offset:8192
	s_or_b64 exec, exec, s[18:19]
	v_cmp_lt_i32_e32 vcc, -1, v130
	v_mov_b32_e32 v47, 0
	v_mov_b32_e32 v46, 0
	v_mov_b32_e32 v45, 0
	v_mov_b32_e32 v44, 0
	v_mov_b32_e32 v43, 0
	v_mov_b32_e32 v42, 0
	v_mov_b32_e32 v41, 0
	v_mov_b32_e32 v40, 0
	v_mov_b32_e32 v39, 0
	v_mov_b32_e32 v38, 0
	v_lshlrev_b32_e32 v125, 2, v22
	v_mov_b32_e32 v37, 0
	v_mov_b32_e32 v36, 0
	v_mov_b32_e32 v35, 0
	v_mov_b32_e32 v34, 0
	v_mov_b32_e32 v33, 0
	v_mov_b32_e32 v32, 0
	v_mov_b32_e32 v31, 0
	v_mov_b32_e32 v30, 0
	v_mov_b32_e32 v29, 0
	v_mov_b32_e32 v28, 0
	v_mov_b32_e32 v27, 0
	v_mov_b32_e32 v26, 0
	v_mov_b32_e32 v25, 0
	v_mov_b32_e32 v24, 0
	v_mov_b32_e32 v23, 0
	v_mov_b32_e32 v22, 0
	s_waitcnt vmcnt(9)
	ds_write_b128 v163, v[6:9]
	s_waitcnt vmcnt(7)
	ds_write_b128 v184, v[10:13]
	v_mov_b32_e32 v21, 0
	v_mov_b32_e32 v20, 0
	v_mov_b32_e32 v19, 0
	v_mov_b32_e32 v18, 0
	v_mov_b32_e32 v17, 0
	v_mov_b32_e32 v16, 0
	v_mov_b32_e32 v10, 0
	s_waitcnt lgkmcnt(0)
	s_barrier
	s_and_saveexec_b64 s[18:19], vcc
	s_cbranch_execz .LBB0_907
	v_mov_b32_e32 v14, v1
	v_mov_b32_e32 v15, v1
	v_lshl_add_u64 v[128:129], v[2:3], 0, v[168:169]
	v_mul_u32_u24_e32 v131, 0x90, v4
	v_mad_u32_u24 v132, v4, s33, v182
	v_mov_b32_e32 v0, v1
	v_mov_b32_e32 v2, v1
	v_mov_b32_e32 v3, v1
	v_mov_b32_e32 v4, v1
	v_mov_b32_e32 v5, v1
	v_mov_b32_e32 v6, v1
	v_mov_b32_e32 v7, v1
	v_mov_b32_e32 v8, v1
	v_mov_b32_e32 v9, v1
	v_mov_b32_e32 v10, v1
	v_mov_b32_e32 v11, v1
	v_mov_b32_e32 v12, v1
	v_mov_b32_e32 v13, v1
	v_mov_b64_e32 v[30:31], v[14:15]
	v_mov_b64_e32 v[46:47], v[14:15]
	v_add_u32_e32 v133, 1, v130
	s_mov_b32 s37, 0
	v_mov_b32_e32 v135, 0xf149f2ca
	v_mov_b32_e32 v134, 0
	s_mov_b64 s[20:21], 0
	v_mov_b64_e32 v[28:29], v[12:13]
	v_mov_b64_e32 v[26:27], v[10:11]
	v_mov_b64_e32 v[24:25], v[8:9]
	v_mov_b64_e32 v[22:23], v[6:7]
	v_mov_b64_e32 v[20:21], v[4:5]
	v_mov_b64_e32 v[18:19], v[2:3]
	v_mov_b64_e32 v[16:17], v[0:1]
	v_mov_b64_e32 v[44:45], v[12:13]
	v_mov_b64_e32 v[42:43], v[10:11]
	v_mov_b64_e32 v[40:41], v[8:9]
	v_mov_b64_e32 v[38:39], v[6:7]
	v_mov_b64_e32 v[36:37], v[4:5]
	v_mov_b64_e32 v[34:35], v[2:3]
	v_mov_b64_e32 v[32:33], v[0:1]
	s_branch .LBB0_902
